# grid barrier: generation kept in a spill lane and L1 invalidate issued right after arrival, on top of the per-XCD write-back
# speedup vs baseline: 1.0037x; 1.0037x over previous
; __device__ __forceinline__ int ltid() { return launder((int)threadIdx.x); }
; __device__ __forceinline__ void prologue(const Params& P) {
;   unsigned char* ws = P.ws; const int tid = ltid();
;   if (blockIdx.x == 0 && tid < 64) {
;     unsigned* ctl = (unsigned*)(ws + WS_CTL);
;     if (tid < 8 || (tid >= 16 && tid < 48)) ctl[tid] = 0u;
; __global__ void __launch_bounds__(512) mega(Params P) {
;   cg::grid_group grid = cg::this_grid();
;   unsigned char* ws = P.ws;
;   if (EN & 1) prologue(P);
;   grid.sync();
_Z4mega6Params:
	s_mov_b32 s96, 0
	v_writelane_b32 v255, s96, 20
	s_mov_b32 s96, 1
	v_writelane_b32 v255, s96, 24
	s_load_dwordx16 s[4:19], s[0:1], 0x40
	s_add_u32 s56, s0, 0xa0
	s_load_dword s52, s[0:1], 0xa0
	s_addc_u32 s57, s1, 0
	v_and_b32_e32 v155, 0x3ff, v0
	s_waitcnt lgkmcnt(0)
	v_writelane_b32 v253, s4, 0
	v_mov_b32_e32 v4, v155
	s_cmp_eq_u32 s2, 0
	v_writelane_b32 v253, s5, 1
	v_writelane_b32 v253, s6, 2
	v_writelane_b32 v253, s7, 3
	v_writelane_b32 v253, s8, 4
	v_writelane_b32 v253, s9, 5
	v_writelane_b32 v253, s10, 6
	v_writelane_b32 v253, s11, 7
	v_writelane_b32 v253, s12, 8
	v_writelane_b32 v253, s13, 9
	v_writelane_b32 v253, s14, 10
	v_writelane_b32 v253, s15, 11
	v_writelane_b32 v253, s16, 12
	v_writelane_b32 v253, s17, 13
	v_writelane_b32 v253, s18, 14
	v_writelane_b32 v253, s19, 15
	s_load_dwordx8 s[4:11], s[0:1], 0x80
	s_mov_b32 s37, s2
	s_cselect_b64 s[2:3], -1, 0
	v_cmp_gt_i32_e32 vcc, 64, v4
	s_waitcnt lgkmcnt(0)
	v_writelane_b32 v253, s4, 16
	s_and_b64 s[2:3], s[2:3], vcc
	s_nop 0
	v_writelane_b32 v253, s5, 17
	v_writelane_b32 v253, s6, 18
	v_writelane_b32 v253, s7, 19
	v_writelane_b32 v253, s8, 20
	v_writelane_b32 v253, s9, 21
	v_writelane_b32 v253, s10, 22
	v_writelane_b32 v253, s11, 23
	s_and_saveexec_b64 s[4:5], s[2:3]
	s_cbranch_execz .LBB0_15
	v_add_u32_e32 v1, -16, v4
	v_cmp_lt_i32_e32 vcc, 7, v4
	v_cmp_lt_u32_e64 s[2:3], 31, v1
	s_and_b64 s[2:3], vcc, s[2:3]
	v_mov_b32_e32 v5, 0
	s_and_saveexec_b64 s[6:7], s[2:3]
	s_xor_b64 s[2:3], exec, s[6:7]
	s_or_saveexec_b64 s[2:3], s[2:3]
	v_mov_b64_e32 v[6:7], v[4:5]
	s_xor_b64 exec, exec, s[2:3]
	s_cbranch_execz .LBB0_3
	s_load_dwordx8 s[8:15], s[0:1], 0x80
	v_ashrrev_i32_e32 v7, 31, v4
	v_mov_b32_e32 v6, v4
	v_mov_b32_e32 v1, 0
	s_waitcnt lgkmcnt(0)
	v_lshl_add_u64 v[2:3], v[6:7], 2, s[14:15]
	global_store_dword v[2:3], v1, off

; __global__ void __launch_bounds__(512) mega(Params P) {
;     ...
;   grid.sync();
.Lgbx_arr_0:
	s_lshl_b32 s1, s1, 2
	s_addk_i32 s1, 0x88
	v_mov_b32_e32 v2, s1
	v_readlane_b32 s98, v255, 20
	s_nop 3
	s_lshl_b32 s99, s98, 16
	v_mov_b32_e32 v0, s99
	s_add_i32 s98, s98, 1
	v_writelane_b32 v255, s98, 20
	v_mov_b32_e32 v3, 1
	s_waitcnt vmcnt(0)
	v_and_b32_e32 v0, 0xffff0000, v0
	global_atomic_add v3, v2, v3, s[4:5] sc0
	s_waitcnt vmcnt(0)
	buffer_inv sc1
	v_and_b32_e32 v3, 0xffff, v3
	s_nop 0
	v_readfirstlane_b32 s1, v3
	s_nop 3
	s_add_i32 s0, s6, -1
	s_cmp_lg_u32 s1, s0
	s_cbranch_scc1 .Lgbx_poll_0
	s_cmp_eq_u32 s96, 0
	s_cbranch_scc0 .Lgbx_nofl_0
	buffer_wbl2 sc1
	s_waitcnt vmcnt(0)

; __global__ void __launch_bounds__(512) mega(Params P) {
;     ...
;   for (int l = 0; l < 2; ++l) {
;     if (l > 0) { norm_phase(H, P.attn_norm + l * DM, HN); grid.sync(); }
;     { EpiIn e; e.cqkv = CQKV; e.ka = (bf16_t*)(ws + WS_KA); e.qd = (bf16_t*)(ws + WS_QD); e.kd = (bf16_t*)(ws + WS_KD); e.vtd = (bf16_t*)(ws + WS_VTD);
;       e.qs = (bf16_t*)(ws + WS_QS); e.ks = (bf16_t*)(ws + WS_KS); e.vts = (bf16_t*)(ws + WS_VTS); e.rope = rope;
;       if (EN & 2) gemm_phase(HN, DM, (const bf16_t*)(ws + WS_WIN) + (size_t)l * N_IN * 1024, 1024, NREAL, N_IN, 1024, e); }
;     grid.sync();
;     { EpiUp e; e.qa = (bf16_t*)(ws + WS_QA); e.ka = (bf16_t*)(ws + WS_KA); e.vta = (bf16_t*)(ws + WS_VTA); e.rope = rope; e.brow = 0; e.rs_direct = 0.f; e.use_direct = 0;
;       if (EN & 4) up_phase(CQKV, (const bf16_t*)(ws + WS_WQB) + (size_t)l * 768 * 256, (const bf16_t*)(ws + WS_WKVB) + (size_t)l * 768 * 256, e); }
;     grid.sync();
;     attn_phase(P, l);
;     grid.sync();
;     if (l == 0) { EpiResid0 e; e.H = H; e.xsrc = P.x; e.msrc = P.meta; gemm_phase(HN, DM, (const bf16_t*)(ws + WS_WOUT), 1024, NREAL, 1024, 1024, e); }
;     else { EpiResid e; e.H = H; gemm_phase(HN, DM, (const bf16_t*)(ws + WS_WOUT) + (size_t)l * 1024 * 1024, 1024, NREAL, 1024, 1024, e); }
;     grid.sync();
;     norm_phase(H, P.ffn_norm + l * DM, HN);
;     grid.sync();
;     if (EN & 128) { EpiGU e; e.act = (bf16_t*)(ws + WS_ACT); gemm_phase(HN, DM, (const bf16_t*)(ws + WS_WGU) + (size_t)l * N_GU * 1024, 1024, NREAL, N_GU, 1024, e); }
;     grid.sync();
;     if (EN & 256) { EpiResid e; e.H = H; gemm_phase((const bf16_t*)(ws + WS_ACT), DFF, (const bf16_t*)(ws + WS_WDN) + (size_t)l * 1024 * DFF, DFF, NREAL, 1024, DFF, e); }
;     grid.sync();
.Lgbx_arr_4:
	s_lshl_b32 s1, s1, 2
	s_addk_i32 s1, 0x88
	v_mov_b32_e32 v2, s1
	v_readlane_b32 s98, v255, 20
	s_nop 3
	s_lshl_b32 s99, s98, 16
	v_mov_b32_e32 v0, s99
	s_add_i32 s98, s98, 1
	v_writelane_b32 v255, s98, 20
	v_mov_b32_e32 v3, 1
	s_waitcnt vmcnt(0)
	v_and_b32_e32 v0, 0xffff0000, v0
	global_atomic_add v3, v2, v3, s[6:7] sc0
	s_waitcnt vmcnt(0)
	buffer_inv sc1
	v_and_b32_e32 v3, 0xffff, v3
	s_nop 0
	v_readfirstlane_b32 s1, v3
	s_nop 3
	s_add_i32 s0, s8, -1
	s_cmp_lg_u32 s1, s0
	s_cbranch_scc1 .Lgbx_poll_4
	s_cmp_eq_u32 s96, 0
	s_cbranch_scc0 .Lgbx_nofl_4
	buffer_wbl2 sc1
	s_waitcnt vmcnt(0)
